# grid barrier: non-leader workgroups poll the cross-XCD release generation directly instead of the per-XCD one (one hop less on the release path)
# speedup vs baseline: 1.0036x; 1.0014x over previous
.LBB0_683:
	s_or_b64 exec, exec, s[0:1]
	v_cvt_f32_u32_e32 v4, v2
	s_waitcnt vmcnt(0)
	v_readfirstlane_b32 s0, v3
	v_sub_u32_e32 v3, 0, v2
	v_rcp_iflag_f32_e32 v4, v4
	v_add_u32_e32 v5, s0, v1
	v_mul_f32_e32 v4, 0x4f7ffffe, v4
	v_cvt_u32_f32_e32 v4, v4
	v_mul_lo_u32 v1, v3, v4
	v_mul_hi_u32 v1, v4, v1
	v_add_u32_e32 v1, v4, v1
	v_mul_hi_u32 v1, v5, v1
	v_mul_lo_u32 v3, v1, v2
	v_sub_u32_e32 v3, v5, v3
	v_add_u32_e32 v4, 1, v1
	v_cmp_ge_u32_e32 vcc, v3, v2
	s_nop 1
	v_cndmask_b32_e32 v1, v1, v4, vcc
	v_sub_u32_e32 v4, v3, v2
	v_cndmask_b32_e32 v3, v3, v4, vcc
	v_add_u32_e32 v4, 1, v1
	v_cmp_ge_u32_e32 vcc, v3, v2
	v_add_u32_e32 v3, 1, v5
	s_nop 0
	v_cndmask_b32_e32 v1, v1, v4, vcc
	v_mul_lo_u32 v4, v2, v1
	v_add_u32_e32 v2, v4, v2
	v_cmp_ne_u32_e32 vcc, v3, v2
	s_and_saveexec_b64 s[0:1], vcc
	s_xor_b64 s[0:1], exec, s[0:1]
	s_cbranch_execz .LBB0_697
	v_readlane_b32 s4, v254, 13
	v_readlane_b32 s5, v254, 14
	s_waitcnt lgkmcnt(0)
	s_nop 3
	global_load_dword v0, v113, s[4:5] sc1
	s_waitcnt vmcnt(0)
	v_cmp_eq_u32_e32 vcc, v0, v1
	s_and_saveexec_b64 s[4:5], vcc
	s_cbranch_execz .LBB0_696
	s_mov_b32 s18, 1
	s_mov_b64 s[6:7], 0
	s_branch .LBB0_687

.LBB0_689:
	v_readlane_b32 s10, v254, 13
	v_readlane_b32 s11, v254, 14
	s_add_i32 s18, s18, 1
	s_mov_b64 s[12:13], -1
	s_nop 2
	global_load_dword v0, v113, s[10:11] sc1
	s_waitcnt vmcnt(0)
	v_cmp_ne_u32_e32 vcc, v0, v1
	s_orn2_b64 s[10:11], vcc, exec
	s_branch .LBB0_686
